# EpiProj: straight-line epilogues for q_B, k_B, v_B and gate column panels (no side outputs), old branchy path kept for rope and tail panels
# speedup vs baseline: 1.0296x; 1.0199x over previous
;     DI void operator()(f32x4 (&acc)[2][2][4][2], const Unit& u, int wr, int wc, int fr, int fq, LAS unsigned char* lds) const {
;     ...
;         const int row0 = u.pm * 256 + wr * 64 + fr, cw = wc * 32 + 8 * fq;
;         const bool rope_wave = (wc & 1) == 0;
;         float rsv[8];
;         { const LAS float* tab = (const LAS float*)(lds + RS_OFF) + u.rk * 256 + wr * 64 + fr;
; #pragma unroll
;           for (int i = 0; i < 8; ++i) rsv[i] = tab[(i >> 2) * 128 + (i & 3) * 16]; }
; #pragma unroll
;         for (int ai = 0; ai < 2; ++ai)
; #pragma unroll
;             for (int m = 0; m < 4; ++m) {
;                 const int row = row0 + ai * 128 + m * 16; const float rs = rsv[ai * 4 + m];
;                 int posidx; long offA, offB;
;                 const bool prm = row < TP;
;                 if (prm) { const int b = row >> 13, t = row & 8191; posidx = t;
;                     offA = t >= 8064 ? ((long)(layer * 4 + b) * 128 + (t - 8064)) * 128 : -1;
;                     offB = t >= 7680 ? ((long)(layer * 4 + b) * 512 + (t - 7680)) * 512 : -1;
;                 } else { const int sb = (row - TP) >> 6, t = (row - TP) & 63; posidx = 8192 + t;
;                     offA = ((long)(layer * 32 + sb) * 128 + 64 + t) * 128;
;                     offB = ((long)(layer * 32 + sb) * 512 + 448 + t) * 512; }
; #pragma unroll
;                 for (int bj = 0; bj < 2; ++bj) {
;                     const int gcol = u.pn * 256 + bj * 128;
;                     f32x4 v0 = acc[ai][bj][m][0] * rs, v1 = acc[ai][bj][m][1] * rs;
;                     if (gcol < 768 && gcol != 640) {
;                         if (rope_wave) {
;                             const float* rp = ROPE + (size_t)posidx * 16;
;                             const f32x4 cs0 = *(const f32x4*)rp, cs1 = *(const f32x4*)(rp + 4), sn0 = *(const f32x4*)(rp + 8), sn1 = *(const f32x4*)(rp + 12);
;                             f32x4 p0, p1;
; #pragma unroll
;                             for (int j = 0; j < 4; ++j) { p0[j] = __shfl_xor(v0[j], 16); p1[j] = __shfl_xor(v1[j], 16); }
;                             if (fq == 0) { v0 = v0 * cs0 - p0 * sn0; v1 = v1 * cs1 - p1 * sn1; }
;                             else if (fq == 1) { v0 = v0 * cs0 + p0 * sn0; v1 = v1 * cs1 + p1 * sn1; }
;                         }
;                     }
;                     bf16_t* dst; int ld, c0; float* of = nullptr; long orow = -1;
.Lrope_pre_skip:
	v_lshl_add_u32 v96, s4, 10, v175
	ds_read2_b32 v[220:221], v96 offset1:16
	ds_read2_b32 v[204:205], v96 offset0:32 offset1:48
	ds_read2_b32 v[198:199], v96 offset0:128 offset1:144
	ds_read2_b32 v[194:195], v96 offset0:160 offset1:176
	v_lshl_add_u32 v192, s96, 8, v171
	s_cmp_gt_i32 s97, 8
	s_cbranch_scc1 .Lepf_gates
	s_cmp_lt_i32 s97, 3
	s_cbranch_scc1 .Lepf_none
	s_cmp_lt_i32 s97, 5
	s_cbranch_scc1 .Lepf_qb
	s_cmpk_gt_i32 s96, 0x7f
	s_cbranch_scc1 .Lepf_none
	s_and_b32 s0, s96, 31
	s_cmp_gt_i32 s0, 29
	s_cbranch_scc1 .Lepf_none
	s_cmp_lt_i32 s97, 7
	s_cbranch_scc1 .Lepf_kb
	v_readlane_b32 s24, v250, 42
	v_readlane_b32 s25, v250, 43
	s_add_i32 s22, s97, -7
	s_lshl_b32 s22, s22, 9
	s_branch .Lepf_plain
.Lepf_kb:
	v_readlane_b32 s24, v250, 46
	v_readlane_b32 s25, v250, 47
	s_add_i32 s22, s97, -5
	s_lshl_b32 s22, s22, 9
.Lepf_plain:
	s_waitcnt lgkmcnt(0)
	v_lshlrev_b32_e32 v154, 10, v192
	v_lshl_add_u32 v154, v166, 1, v154
	v_add_u32_e32 v154, s22, v154
	v_mul_f32_e32 v146, v126, v220
	v_mul_f32_e32 v147, v127, v220
	v_mul_f32_e32 v148, v128, v220
	v_mul_f32_e32 v149, v129, v220
	v_mul_f32_e32 v150, v122, v220
	v_mul_f32_e32 v151, v123, v220
	v_mul_f32_e32 v152, v124, v220
	v_mul_f32_e32 v153, v125, v220
	v_add_u32_e32 v156, 0x0, v154
	s_nop 0
	v_cvt_pk_bf16_f32 v206, v146, v147
	v_cvt_pk_bf16_f32 v207, v148, v149
	v_cvt_pk_bf16_f32 v208, v150, v151
	v_cvt_pk_bf16_f32 v209, v152, v153
	global_store_dwordx4 v156, v[206:209], s[24:25]
	v_mul_f32_e32 v146, v92, v220
	v_mul_f32_e32 v147, v93, v220
	v_mul_f32_e32 v148, v94, v220
	v_mul_f32_e32 v149, v95, v220
	v_mul_f32_e32 v150, v88, v220
	v_mul_f32_e32 v151, v89, v220
	v_mul_f32_e32 v152, v90, v220
	v_mul_f32_e32 v153, v91, v220
	v_add_u32_e32 v156, 0x100, v154
	s_nop 0
	v_cvt_pk_bf16_f32 v210, v146, v147
	v_cvt_pk_bf16_f32 v211, v148, v149
	v_cvt_pk_bf16_f32 v212, v150, v151
	v_cvt_pk_bf16_f32 v213, v152, v153
	global_store_dwordx4 v156, v[210:213], s[24:25]
	v_mul_f32_e32 v146, v118, v221
	v_mul_f32_e32 v147, v119, v221
	v_mul_f32_e32 v148, v120, v221
	v_mul_f32_e32 v149, v121, v221
	v_mul_f32_e32 v150, v114, v221
	v_mul_f32_e32 v151, v115, v221
	v_mul_f32_e32 v152, v116, v221
	v_mul_f32_e32 v153, v117, v221
	v_add_u32_e32 v156, 0x4000, v154
	s_nop 0
	v_cvt_pk_bf16_f32 v206, v146, v147
	v_cvt_pk_bf16_f32 v207, v148, v149
	v_cvt_pk_bf16_f32 v208, v150, v151
	v_cvt_pk_bf16_f32 v209, v152, v153
	global_store_dwordx4 v156, v[206:209], s[24:25]
	v_mul_f32_e32 v146, v84, v221
	v_mul_f32_e32 v147, v85, v221
	v_mul_f32_e32 v148, v86, v221
	v_mul_f32_e32 v149, v87, v221
	v_mul_f32_e32 v150, v80, v221
	v_mul_f32_e32 v151, v81, v221
	v_mul_f32_e32 v152, v82, v221
	v_mul_f32_e32 v153, v83, v221
	v_add_u32_e32 v156, 0x4100, v154
	s_nop 0
	v_cvt_pk_bf16_f32 v210, v146, v147
	v_cvt_pk_bf16_f32 v211, v148, v149
	v_cvt_pk_bf16_f32 v212, v150, v151
	v_cvt_pk_bf16_f32 v213, v152, v153
	global_store_dwordx4 v156, v[210:213], s[24:25]
	v_mul_f32_e32 v146, v110, v204
	v_mul_f32_e32 v147, v111, v204
	v_mul_f32_e32 v148, v112, v204
	v_mul_f32_e32 v149, v113, v204
	v_mul_f32_e32 v150, v106, v204
	v_mul_f32_e32 v151, v107, v204
	v_mul_f32_e32 v152, v108, v204
	v_mul_f32_e32 v153, v109, v204
	v_add_u32_e32 v156, 0x8000, v154
	s_nop 0
	v_cvt_pk_bf16_f32 v206, v146, v147
	v_cvt_pk_bf16_f32 v207, v148, v149
	v_cvt_pk_bf16_f32 v208, v150, v151
	v_cvt_pk_bf16_f32 v209, v152, v153
	global_store_dwordx4 v156, v[206:209], s[24:25]
	v_mul_f32_e32 v146, v76, v204
	v_mul_f32_e32 v147, v77, v204
	v_mul_f32_e32 v148, v78, v204
	v_mul_f32_e32 v149, v79, v204
	v_mul_f32_e32 v150, v72, v204
	v_mul_f32_e32 v151, v73, v204
	v_mul_f32_e32 v152, v74, v204
	v_mul_f32_e32 v153, v75, v204
	v_add_u32_e32 v156, 0x8100, v154
	s_nop 0
	v_cvt_pk_bf16_f32 v210, v146, v147
	v_cvt_pk_bf16_f32 v211, v148, v149
	v_cvt_pk_bf16_f32 v212, v150, v151
	v_cvt_pk_bf16_f32 v213, v152, v153
	global_store_dwordx4 v156, v[210:213], s[24:25]
	v_mul_f32_e32 v146, v102, v205
	v_mul_f32_e32 v147, v103, v205
	v_mul_f32_e32 v148, v104, v205
	v_mul_f32_e32 v149, v105, v205
	v_mul_f32_e32 v150, v98, v205
	v_mul_f32_e32 v151, v99, v205
	v_mul_f32_e32 v152, v100, v205
	v_mul_f32_e32 v153, v101, v205
	v_add_u32_e32 v156, 0xc000, v154
	s_nop 0
	v_cvt_pk_bf16_f32 v206, v146, v147
	v_cvt_pk_bf16_f32 v207, v148, v149
	v_cvt_pk_bf16_f32 v208, v150, v151
	v_cvt_pk_bf16_f32 v209, v152, v153
	global_store_dwordx4 v156, v[206:209], s[24:25]
	v_mul_f32_e32 v146, v68, v205
	v_mul_f32_e32 v147, v69, v205
	v_mul_f32_e32 v148, v70, v205
	v_mul_f32_e32 v149, v71, v205
	v_mul_f32_e32 v150, v64, v205
	v_mul_f32_e32 v151, v65, v205
	v_mul_f32_e32 v152, v66, v205
	v_mul_f32_e32 v153, v67, v205
	v_add_u32_e32 v156, 0xc100, v154
	s_nop 0
	v_cvt_pk_bf16_f32 v210, v146, v147
	v_cvt_pk_bf16_f32 v211, v148, v149
	v_cvt_pk_bf16_f32 v212, v150, v151
	v_cvt_pk_bf16_f32 v213, v152, v153
	global_store_dwordx4 v156, v[210:213], s[24:25]
	v_mul_f32_e32 v146, v60, v198
	v_mul_f32_e32 v147, v61, v198
	v_mul_f32_e32 v148, v62, v198
	v_mul_f32_e32 v149, v63, v198
	v_mul_f32_e32 v150, v56, v198
	v_mul_f32_e32 v151, v57, v198
	v_mul_f32_e32 v152, v58, v198
	v_mul_f32_e32 v153, v59, v198
	v_add_u32_e32 v156, 0x20000, v154
	s_nop 0
	v_cvt_pk_bf16_f32 v206, v146, v147
	v_cvt_pk_bf16_f32 v207, v148, v149
	v_cvt_pk_bf16_f32 v208, v150, v151
	v_cvt_pk_bf16_f32 v209, v152, v153
	global_store_dwordx4 v156, v[206:209], s[24:25]
	v_mul_f32_e32 v146, v28, v198
	v_mul_f32_e32 v147, v29, v198
	v_mul_f32_e32 v148, v30, v198
	v_mul_f32_e32 v149, v31, v198
	v_mul_f32_e32 v150, v24, v198
	v_mul_f32_e32 v151, v25, v198
	v_mul_f32_e32 v152, v26, v198
	v_mul_f32_e32 v153, v27, v198
	v_add_u32_e32 v156, 0x20100, v154
; #define LAS __attribute__((address_space(3)))
; DI unsigned pk2(float lo, float hi) { f32x2 v = {lo, hi}; hbf2 r = __builtin_convertvector(v, hbf2); return __builtin_bit_cast(unsigned, r); }
; DI float sigmoidf_(float a) { return fast_rcp(1.0f + fast_exp2(-a * LOG2E)); }
;     DI void operator()(f32x4 (&acc)[2][2][4][2], const Unit& u, int wr, int wc, int fr, int fq, LAS unsigned char* lds) const {
;     ...
;                     bf16_t* dst; int ld, c0; float* of = nullptr; long orow = -1;
;                     if (gcol < 512) { dst = QA; ld = 512; c0 = gcol; v0 = v0 * QSCALE; v1 = v1 * QSCALE; }
;                     else if (gcol < 640) { dst = KA; ld = 128; c0 = gcol - 512; of = out + (prm ? O_KWP : O_KWS); orow = offA; }
;                     else if (gcol < 768) { dst = VA; ld = 128; c0 = gcol - 640; of = out + (prm ? O_VWP : O_VWS); orow = offA; }
;                     else if (gcol < 1280) { dst = QB; ld = 512; c0 = gcol - 768; v0 = v0 * QSCALE; v1 = v1 * QSCALE; }
;                     else if (gcol < 1792) { dst = KB; ld = 512; c0 = gcol - 1280; of = out + (prm ? O_KBP : O_KBS); orow = offB; }
;                     else if (gcol < 2304) { dst = VB; ld = 512; c0 = gcol - 1792; of = out + (prm ? O_VBP : O_VBS); orow = offB; }
;                     else { dst = GATES; ld = 2048; c0 = gcol - 2304;
;                         const f32x4 g0 = *(const LAS f32x4*)(lds + BG_OFF + (c0 + cw) * 4), g1 = *(const LAS f32x4*)(lds + BG_OFF + (c0 + cw + 4) * 4);
; #pragma unroll
;                         for (int j = 0; j < 4; ++j) { v0[j] = sigmoidf_(v0[j] + g0[j]); v1[j] = sigmoidf_(v1[j] + g1[j]); } }
;                     u32x4 w; w.x = pk2(v0[0], v0[1]); w.y = pk2(v0[2], v0[3]); w.z = pk2(v1[0], v1[1]); w.w = pk2(v1[2], v1[3]);
;                     *(u32x4*)(dst + (size_t)row * ld + c0 + cw) = w;
	s_nop 0
	v_cvt_pk_bf16_f32 v210, v146, v147
	v_cvt_pk_bf16_f32 v211, v148, v149
	v_cvt_pk_bf16_f32 v212, v150, v151
	v_cvt_pk_bf16_f32 v213, v152, v153
	global_store_dwordx4 v156, v[210:213], s[24:25]
	v_mul_f32_e32 v146, v52, v199
	v_mul_f32_e32 v147, v53, v199
	v_mul_f32_e32 v148, v54, v199
	v_mul_f32_e32 v149, v55, v199
	v_mul_f32_e32 v150, v48, v199
	v_mul_f32_e32 v151, v49, v199
	v_mul_f32_e32 v152, v50, v199
	v_mul_f32_e32 v153, v51, v199
	v_add_u32_e32 v156, 0x24000, v154
	s_nop 0
	v_cvt_pk_bf16_f32 v206, v146, v147
	v_cvt_pk_bf16_f32 v207, v148, v149
	v_cvt_pk_bf16_f32 v208, v150, v151
	v_cvt_pk_bf16_f32 v209, v152, v153
	global_store_dwordx4 v156, v[206:209], s[24:25]
	v_mul_f32_e32 v146, v20, v199
	v_mul_f32_e32 v147, v21, v199
	v_mul_f32_e32 v148, v22, v199
	v_mul_f32_e32 v149, v23, v199
	v_mul_f32_e32 v150, v16, v199
	v_mul_f32_e32 v151, v17, v199
	v_mul_f32_e32 v152, v18, v199
	v_mul_f32_e32 v153, v19, v199
	v_add_u32_e32 v156, 0x24100, v154
	s_nop 0
	v_cvt_pk_bf16_f32 v210, v146, v147
	v_cvt_pk_bf16_f32 v211, v148, v149
	v_cvt_pk_bf16_f32 v212, v150, v151
	v_cvt_pk_bf16_f32 v213, v152, v153
	global_store_dwordx4 v156, v[210:213], s[24:25]
	v_mul_f32_e32 v146, v44, v194
	v_mul_f32_e32 v147, v45, v194
	v_mul_f32_e32 v148, v46, v194
	v_mul_f32_e32 v149, v47, v194
	v_mul_f32_e32 v150, v40, v194
	v_mul_f32_e32 v151, v41, v194
	v_mul_f32_e32 v152, v42, v194
	v_mul_f32_e32 v153, v43, v194
	v_add_u32_e32 v156, 0x28000, v154
	s_nop 0
	v_cvt_pk_bf16_f32 v206, v146, v147
	v_cvt_pk_bf16_f32 v207, v148, v149
	v_cvt_pk_bf16_f32 v208, v150, v151
	v_cvt_pk_bf16_f32 v209, v152, v153
	global_store_dwordx4 v156, v[206:209], s[24:25]
	v_mul_f32_e32 v146, v12, v194
	v_mul_f32_e32 v147, v13, v194
	v_mul_f32_e32 v148, v14, v194
	v_mul_f32_e32 v149, v15, v194
	v_mul_f32_e32 v150, v8, v194
	v_mul_f32_e32 v151, v9, v194
	v_mul_f32_e32 v152, v10, v194
	v_mul_f32_e32 v153, v11, v194
	v_add_u32_e32 v156, 0x28100, v154
	s_nop 0
	v_cvt_pk_bf16_f32 v210, v146, v147
	v_cvt_pk_bf16_f32 v211, v148, v149
	v_cvt_pk_bf16_f32 v212, v150, v151
	v_cvt_pk_bf16_f32 v213, v152, v153
	global_store_dwordx4 v156, v[210:213], s[24:25]
	v_mul_f32_e32 v146, v36, v195
	v_mul_f32_e32 v147, v37, v195
	v_mul_f32_e32 v148, v38, v195
	v_mul_f32_e32 v149, v39, v195
	v_mul_f32_e32 v150, v32, v195
	v_mul_f32_e32 v151, v33, v195
	v_mul_f32_e32 v152, v34, v195
	v_mul_f32_e32 v153, v35, v195
	v_add_u32_e32 v156, 0x2c000, v154
	s_nop 0
	v_cvt_pk_bf16_f32 v206, v146, v147
	v_cvt_pk_bf16_f32 v207, v148, v149
	v_cvt_pk_bf16_f32 v208, v150, v151
	v_cvt_pk_bf16_f32 v209, v152, v153
	global_store_dwordx4 v156, v[206:209], s[24:25]
	v_mul_f32_e32 v146, v4, v195
	v_mul_f32_e32 v147, v5, v195
	v_mul_f32_e32 v148, v6, v195
	v_mul_f32_e32 v149, v7, v195
	v_mul_f32_e32 v150, v0, v195
	v_mul_f32_e32 v151, v1, v195
	v_mul_f32_e32 v152, v2, v195
	v_mul_f32_e32 v153, v3, v195
	v_add_u32_e32 v156, 0x2c100, v154
	s_nop 0
	v_cvt_pk_bf16_f32 v210, v146, v147
	v_cvt_pk_bf16_f32 v211, v148, v149
	v_cvt_pk_bf16_f32 v212, v150, v151
	v_cvt_pk_bf16_f32 v213, v152, v153
	global_store_dwordx4 v156, v[210:213], s[24:25]
	s_mov_b64 s[22:23], exec
	s_branch .LBB0_639
.Lepf_qb:
	v_readlane_b32 s24, v250, 44
	v_readlane_b32 s25, v250, 45
	s_add_i32 s22, s97, -3
	s_lshl_b32 s22, s22, 9
	s_waitcnt lgkmcnt(0)
	v_lshlrev_b32_e32 v154, 10, v192
	v_lshl_add_u32 v154, v166, 1, v154
	v_add_u32_e32 v154, s22, v154
	v_mul_f32_e32 v146, v126, v220
	v_mul_f32_e32 v147, v127, v220
	v_mul_f32_e32 v148, v128, v220
	v_mul_f32_e32 v149, v129, v220
	v_mul_f32_e32 v150, v122, v220
	v_mul_f32_e32 v151, v123, v220
	v_mul_f32_e32 v152, v124, v220
	v_mul_f32_e32 v153, v125, v220
	v_mul_f32_e32 v146, s66, v146
	v_mul_f32_e32 v147, s66, v147
	v_mul_f32_e32 v148, s66, v148
	v_mul_f32_e32 v149, s66, v149
	v_mul_f32_e32 v150, s66, v150
	v_mul_f32_e32 v151, s66, v151
	v_mul_f32_e32 v152, s66, v152
	v_mul_f32_e32 v153, s66, v153
	v_add_u32_e32 v156, 0x0, v154
	v_cvt_pk_bf16_f32 v206, v146, v147
	v_cvt_pk_bf16_f32 v207, v148, v149
	v_cvt_pk_bf16_f32 v208, v150, v151
	v_cvt_pk_bf16_f32 v209, v152, v153
	global_store_dwordx4 v156, v[206:209], s[24:25]
	v_mul_f32_e32 v146, v92, v220
	v_mul_f32_e32 v147, v93, v220
	v_mul_f32_e32 v148, v94, v220
	v_mul_f32_e32 v149, v95, v220
	v_mul_f32_e32 v150, v88, v220
	v_mul_f32_e32 v151, v89, v220
	v_mul_f32_e32 v152, v90, v220
	v_mul_f32_e32 v153, v91, v220
	v_mul_f32_e32 v146, s66, v146
	v_mul_f32_e32 v147, s66, v147
	v_mul_f32_e32 v148, s66, v148
	v_mul_f32_e32 v149, s66, v149
	v_mul_f32_e32 v150, s66, v150
	v_mul_f32_e32 v151, s66, v151
	v_mul_f32_e32 v152, s66, v152
	v_mul_f32_e32 v153, s66, v153
	v_add_u32_e32 v156, 0x100, v154
	v_cvt_pk_bf16_f32 v210, v146, v147
	v_cvt_pk_bf16_f32 v211, v148, v149
	v_cvt_pk_bf16_f32 v212, v150, v151
	v_cvt_pk_bf16_f32 v213, v152, v153
	global_store_dwordx4 v156, v[210:213], s[24:25]
	v_mul_f32_e32 v146, v118, v221
	v_mul_f32_e32 v147, v119, v221
	v_mul_f32_e32 v148, v120, v221
	v_mul_f32_e32 v149, v121, v221
	v_mul_f32_e32 v150, v114, v221
	v_mul_f32_e32 v151, v115, v221
	v_mul_f32_e32 v152, v116, v221
	v_mul_f32_e32 v153, v117, v221
	v_mul_f32_e32 v146, s66, v146
	v_mul_f32_e32 v147, s66, v147
	v_mul_f32_e32 v148, s66, v148
	v_mul_f32_e32 v149, s66, v149
	v_mul_f32_e32 v150, s66, v150
	v_mul_f32_e32 v151, s66, v151
	v_mul_f32_e32 v152, s66, v152
	v_mul_f32_e32 v153, s66, v153
	v_add_u32_e32 v156, 0x4000, v154
	v_cvt_pk_bf16_f32 v206, v146, v147
	v_cvt_pk_bf16_f32 v207, v148, v149
	v_cvt_pk_bf16_f32 v208, v150, v151
	v_cvt_pk_bf16_f32 v209, v152, v153
	global_store_dwordx4 v156, v[206:209], s[24:25]
	v_mul_f32_e32 v146, v84, v221
	v_mul_f32_e32 v147, v85, v221
; #define LAS __attribute__((address_space(3)))
; DI unsigned pk2(float lo, float hi) { f32x2 v = {lo, hi}; hbf2 r = __builtin_convertvector(v, hbf2); return __builtin_bit_cast(unsigned, r); }
; DI float sigmoidf_(float a) { return fast_rcp(1.0f + fast_exp2(-a * LOG2E)); }
;     DI void operator()(f32x4 (&acc)[2][2][4][2], const Unit& u, int wr, int wc, int fr, int fq, LAS unsigned char* lds) const {
;     ...
;                     else if (gcol < 1280) { dst = QB; ld = 512; c0 = gcol - 768; v0 = v0 * QSCALE; v1 = v1 * QSCALE; }
;                     else if (gcol < 1792) { dst = KB; ld = 512; c0 = gcol - 1280; of = out + (prm ? O_KBP : O_KBS); orow = offB; }
;                     else if (gcol < 2304) { dst = VB; ld = 512; c0 = gcol - 1792; of = out + (prm ? O_VBP : O_VBS); orow = offB; }
;                     else { dst = GATES; ld = 2048; c0 = gcol - 2304;
;                         const f32x4 g0 = *(const LAS f32x4*)(lds + BG_OFF + (c0 + cw) * 4), g1 = *(const LAS f32x4*)(lds + BG_OFF + (c0 + cw + 4) * 4);
; #pragma unroll
;                         for (int j = 0; j < 4; ++j) { v0[j] = sigmoidf_(v0[j] + g0[j]); v1[j] = sigmoidf_(v1[j] + g1[j]); } }
;                     u32x4 w; w.x = pk2(v0[0], v0[1]); w.y = pk2(v0[2], v0[3]); w.z = pk2(v1[0], v1[1]); w.w = pk2(v1[2], v1[3]);
;                     *(u32x4*)(dst + (size_t)row * ld + c0 + cw) = w;
	v_mul_f32_e32 v148, v86, v221
	v_mul_f32_e32 v149, v87, v221
	v_mul_f32_e32 v150, v80, v221
	v_mul_f32_e32 v151, v81, v221
	v_mul_f32_e32 v152, v82, v221
	v_mul_f32_e32 v153, v83, v221
	v_mul_f32_e32 v146, s66, v146
	v_mul_f32_e32 v147, s66, v147
	v_mul_f32_e32 v148, s66, v148
	v_mul_f32_e32 v149, s66, v149
	v_mul_f32_e32 v150, s66, v150
	v_mul_f32_e32 v151, s66, v151
	v_mul_f32_e32 v152, s66, v152
	v_mul_f32_e32 v153, s66, v153
	v_add_u32_e32 v156, 0x4100, v154
	v_cvt_pk_bf16_f32 v210, v146, v147
	v_cvt_pk_bf16_f32 v211, v148, v149
	v_cvt_pk_bf16_f32 v212, v150, v151
	v_cvt_pk_bf16_f32 v213, v152, v153
	global_store_dwordx4 v156, v[210:213], s[24:25]
	v_mul_f32_e32 v146, v110, v204
	v_mul_f32_e32 v147, v111, v204
	v_mul_f32_e32 v148, v112, v204
	v_mul_f32_e32 v149, v113, v204
	v_mul_f32_e32 v150, v106, v204
	v_mul_f32_e32 v151, v107, v204
	v_mul_f32_e32 v152, v108, v204
	v_mul_f32_e32 v153, v109, v204
	v_mul_f32_e32 v146, s66, v146
	v_mul_f32_e32 v147, s66, v147
	v_mul_f32_e32 v148, s66, v148
	v_mul_f32_e32 v149, s66, v149
	v_mul_f32_e32 v150, s66, v150
	v_mul_f32_e32 v151, s66, v151
	v_mul_f32_e32 v152, s66, v152
	v_mul_f32_e32 v153, s66, v153
	v_add_u32_e32 v156, 0x8000, v154
	v_cvt_pk_bf16_f32 v206, v146, v147
	v_cvt_pk_bf16_f32 v207, v148, v149
	v_cvt_pk_bf16_f32 v208, v150, v151
	v_cvt_pk_bf16_f32 v209, v152, v153
	global_store_dwordx4 v156, v[206:209], s[24:25]
	v_mul_f32_e32 v146, v76, v204
	v_mul_f32_e32 v147, v77, v204
	v_mul_f32_e32 v148, v78, v204
	v_mul_f32_e32 v149, v79, v204
	v_mul_f32_e32 v150, v72, v204
	v_mul_f32_e32 v151, v73, v204
	v_mul_f32_e32 v152, v74, v204
	v_mul_f32_e32 v153, v75, v204
	v_mul_f32_e32 v146, s66, v146
	v_mul_f32_e32 v147, s66, v147
	v_mul_f32_e32 v148, s66, v148
	v_mul_f32_e32 v149, s66, v149
	v_mul_f32_e32 v150, s66, v150
	v_mul_f32_e32 v151, s66, v151
	v_mul_f32_e32 v152, s66, v152
	v_mul_f32_e32 v153, s66, v153
	v_add_u32_e32 v156, 0x8100, v154
	v_cvt_pk_bf16_f32 v210, v146, v147
	v_cvt_pk_bf16_f32 v211, v148, v149
	v_cvt_pk_bf16_f32 v212, v150, v151
	v_cvt_pk_bf16_f32 v213, v152, v153
	global_store_dwordx4 v156, v[210:213], s[24:25]
	v_mul_f32_e32 v146, v102, v205
	v_mul_f32_e32 v147, v103, v205
	v_mul_f32_e32 v148, v104, v205
	v_mul_f32_e32 v149, v105, v205
	v_mul_f32_e32 v150, v98, v205
	v_mul_f32_e32 v151, v99, v205
	v_mul_f32_e32 v152, v100, v205
	v_mul_f32_e32 v153, v101, v205
	v_mul_f32_e32 v146, s66, v146
	v_mul_f32_e32 v147, s66, v147
	v_mul_f32_e32 v148, s66, v148
	v_mul_f32_e32 v149, s66, v149
	v_mul_f32_e32 v150, s66, v150
	v_mul_f32_e32 v151, s66, v151
	v_mul_f32_e32 v152, s66, v152
	v_mul_f32_e32 v153, s66, v153
	v_add_u32_e32 v156, 0xc000, v154
	v_cvt_pk_bf16_f32 v206, v146, v147
	v_cvt_pk_bf16_f32 v207, v148, v149
	v_cvt_pk_bf16_f32 v208, v150, v151
	v_cvt_pk_bf16_f32 v209, v152, v153
	global_store_dwordx4 v156, v[206:209], s[24:25]
	v_mul_f32_e32 v146, v68, v205
	v_mul_f32_e32 v147, v69, v205
	v_mul_f32_e32 v148, v70, v205
	v_mul_f32_e32 v149, v71, v205
	v_mul_f32_e32 v150, v64, v205
	v_mul_f32_e32 v151, v65, v205
	v_mul_f32_e32 v152, v66, v205
	v_mul_f32_e32 v153, v67, v205
	v_mul_f32_e32 v146, s66, v146
	v_mul_f32_e32 v147, s66, v147
	v_mul_f32_e32 v148, s66, v148
	v_mul_f32_e32 v149, s66, v149
	v_mul_f32_e32 v150, s66, v150
	v_mul_f32_e32 v151, s66, v151
	v_mul_f32_e32 v152, s66, v152
	v_mul_f32_e32 v153, s66, v153
	v_add_u32_e32 v156, 0xc100, v154
	v_cvt_pk_bf16_f32 v210, v146, v147
	v_cvt_pk_bf16_f32 v211, v148, v149
	v_cvt_pk_bf16_f32 v212, v150, v151
	v_cvt_pk_bf16_f32 v213, v152, v153
	global_store_dwordx4 v156, v[210:213], s[24:25]
	v_mul_f32_e32 v146, v60, v198
	v_mul_f32_e32 v147, v61, v198
	v_mul_f32_e32 v148, v62, v198
	v_mul_f32_e32 v149, v63, v198
	v_mul_f32_e32 v150, v56, v198
	v_mul_f32_e32 v151, v57, v198
	v_mul_f32_e32 v152, v58, v198
	v_mul_f32_e32 v153, v59, v198
	v_mul_f32_e32 v146, s66, v146
	v_mul_f32_e32 v147, s66, v147
	v_mul_f32_e32 v148, s66, v148
	v_mul_f32_e32 v149, s66, v149
	v_mul_f32_e32 v150, s66, v150
	v_mul_f32_e32 v151, s66, v151
	v_mul_f32_e32 v152, s66, v152
	v_mul_f32_e32 v153, s66, v153
	v_add_u32_e32 v156, 0x20000, v154
	v_cvt_pk_bf16_f32 v206, v146, v147
	v_cvt_pk_bf16_f32 v207, v148, v149
	v_cvt_pk_bf16_f32 v208, v150, v151
	v_cvt_pk_bf16_f32 v209, v152, v153
	global_store_dwordx4 v156, v[206:209], s[24:25]
	v_mul_f32_e32 v146, v28, v198
	v_mul_f32_e32 v147, v29, v198
	v_mul_f32_e32 v148, v30, v198
	v_mul_f32_e32 v149, v31, v198
	v_mul_f32_e32 v150, v24, v198
	v_mul_f32_e32 v151, v25, v198
	v_mul_f32_e32 v152, v26, v198
	v_mul_f32_e32 v153, v27, v198
	v_mul_f32_e32 v146, s66, v146
	v_mul_f32_e32 v147, s66, v147
	v_mul_f32_e32 v148, s66, v148
	v_mul_f32_e32 v149, s66, v149
	v_mul_f32_e32 v150, s66, v150
	v_mul_f32_e32 v151, s66, v151
	v_mul_f32_e32 v152, s66, v152
	v_mul_f32_e32 v153, s66, v153
	v_add_u32_e32 v156, 0x20100, v154
	v_cvt_pk_bf16_f32 v210, v146, v147
	v_cvt_pk_bf16_f32 v211, v148, v149
	v_cvt_pk_bf16_f32 v212, v150, v151
	v_cvt_pk_bf16_f32 v213, v152, v153
	global_store_dwordx4 v156, v[210:213], s[24:25]
	v_mul_f32_e32 v146, v52, v199
	v_mul_f32_e32 v147, v53, v199
	v_mul_f32_e32 v148, v54, v199
	v_mul_f32_e32 v149, v55, v199
	v_mul_f32_e32 v150, v48, v199
	v_mul_f32_e32 v151, v49, v199
	v_mul_f32_e32 v152, v50, v199
	v_mul_f32_e32 v153, v51, v199
	v_mul_f32_e32 v146, s66, v146
	v_mul_f32_e32 v147, s66, v147
	v_mul_f32_e32 v148, s66, v148
	v_mul_f32_e32 v149, s66, v149
	v_mul_f32_e32 v150, s66, v150
	v_mul_f32_e32 v151, s66, v151
	v_mul_f32_e32 v152, s66, v152
	v_mul_f32_e32 v153, s66, v153
	v_add_u32_e32 v156, 0x24000, v154
	v_cvt_pk_bf16_f32 v206, v146, v147
	v_cvt_pk_bf16_f32 v207, v148, v149
	v_cvt_pk_bf16_f32 v208, v150, v151
; #define LAS __attribute__((address_space(3)))
; DI float sigmoidf_(float a) { return fast_rcp(1.0f + fast_exp2(-a * LOG2E)); }
;     DI void operator()(f32x4 (&acc)[2][2][4][2], const Unit& u, int wr, int wc, int fr, int fq, LAS unsigned char* lds) const {
;     ...
;                     else if (gcol < 1280) { dst = QB; ld = 512; c0 = gcol - 768; v0 = v0 * QSCALE; v1 = v1 * QSCALE; }
;                     else if (gcol < 1792) { dst = KB; ld = 512; c0 = gcol - 1280; of = out + (prm ? O_KBP : O_KBS); orow = offB; }
;                     else if (gcol < 2304) { dst = VB; ld = 512; c0 = gcol - 1792; of = out + (prm ? O_VBP : O_VBS); orow = offB; }
;                     else { dst = GATES; ld = 2048; c0 = gcol - 2304;
;                         const f32x4 g0 = *(const LAS f32x4*)(lds + BG_OFF + (c0 + cw) * 4), g1 = *(const LAS f32x4*)(lds + BG_OFF + (c0 + cw + 4) * 4);
; #pragma unroll
;                         for (int j = 0; j < 4; ++j) { v0[j] = sigmoidf_(v0[j] + g0[j]); v1[j] = sigmoidf_(v1[j] + g1[j]); } }
	v_cvt_pk_bf16_f32 v209, v152, v153
	global_store_dwordx4 v156, v[206:209], s[24:25]
	v_mul_f32_e32 v146, v20, v199
	v_mul_f32_e32 v147, v21, v199
	v_mul_f32_e32 v148, v22, v199
	v_mul_f32_e32 v149, v23, v199
	v_mul_f32_e32 v150, v16, v199
	v_mul_f32_e32 v151, v17, v199
	v_mul_f32_e32 v152, v18, v199
	v_mul_f32_e32 v153, v19, v199
	v_mul_f32_e32 v146, s66, v146
	v_mul_f32_e32 v147, s66, v147
	v_mul_f32_e32 v148, s66, v148
	v_mul_f32_e32 v149, s66, v149
	v_mul_f32_e32 v150, s66, v150
	v_mul_f32_e32 v151, s66, v151
	v_mul_f32_e32 v152, s66, v152
	v_mul_f32_e32 v153, s66, v153
	v_add_u32_e32 v156, 0x24100, v154
	v_cvt_pk_bf16_f32 v210, v146, v147
	v_cvt_pk_bf16_f32 v211, v148, v149
	v_cvt_pk_bf16_f32 v212, v150, v151
	v_cvt_pk_bf16_f32 v213, v152, v153
	global_store_dwordx4 v156, v[210:213], s[24:25]
	v_mul_f32_e32 v146, v44, v194
	v_mul_f32_e32 v147, v45, v194
	v_mul_f32_e32 v148, v46, v194
	v_mul_f32_e32 v149, v47, v194
	v_mul_f32_e32 v150, v40, v194
	v_mul_f32_e32 v151, v41, v194
	v_mul_f32_e32 v152, v42, v194
	v_mul_f32_e32 v153, v43, v194
	v_mul_f32_e32 v146, s66, v146
	v_mul_f32_e32 v147, s66, v147
	v_mul_f32_e32 v148, s66, v148
	v_mul_f32_e32 v149, s66, v149
	v_mul_f32_e32 v150, s66, v150
	v_mul_f32_e32 v151, s66, v151
	v_mul_f32_e32 v152, s66, v152
	v_mul_f32_e32 v153, s66, v153
	v_add_u32_e32 v156, 0x28000, v154
	v_cvt_pk_bf16_f32 v206, v146, v147
	v_cvt_pk_bf16_f32 v207, v148, v149
	v_cvt_pk_bf16_f32 v208, v150, v151
	v_cvt_pk_bf16_f32 v209, v152, v153
	global_store_dwordx4 v156, v[206:209], s[24:25]
	v_mul_f32_e32 v146, v12, v194
	v_mul_f32_e32 v147, v13, v194
	v_mul_f32_e32 v148, v14, v194
	v_mul_f32_e32 v149, v15, v194
	v_mul_f32_e32 v150, v8, v194
	v_mul_f32_e32 v151, v9, v194
	v_mul_f32_e32 v152, v10, v194
	v_mul_f32_e32 v153, v11, v194
	v_mul_f32_e32 v146, s66, v146
	v_mul_f32_e32 v147, s66, v147
	v_mul_f32_e32 v148, s66, v148
	v_mul_f32_e32 v149, s66, v149
	v_mul_f32_e32 v150, s66, v150
	v_mul_f32_e32 v151, s66, v151
	v_mul_f32_e32 v152, s66, v152
	v_mul_f32_e32 v153, s66, v153
	v_add_u32_e32 v156, 0x28100, v154
	v_cvt_pk_bf16_f32 v210, v146, v147
	v_cvt_pk_bf16_f32 v211, v148, v149
	v_cvt_pk_bf16_f32 v212, v150, v151
	v_cvt_pk_bf16_f32 v213, v152, v153
	global_store_dwordx4 v156, v[210:213], s[24:25]
	v_mul_f32_e32 v146, v36, v195
	v_mul_f32_e32 v147, v37, v195
	v_mul_f32_e32 v148, v38, v195
	v_mul_f32_e32 v149, v39, v195
	v_mul_f32_e32 v150, v32, v195
	v_mul_f32_e32 v151, v33, v195
	v_mul_f32_e32 v152, v34, v195
	v_mul_f32_e32 v153, v35, v195
	v_mul_f32_e32 v146, s66, v146
	v_mul_f32_e32 v147, s66, v147
	v_mul_f32_e32 v148, s66, v148
	v_mul_f32_e32 v149, s66, v149
	v_mul_f32_e32 v150, s66, v150
	v_mul_f32_e32 v151, s66, v151
	v_mul_f32_e32 v152, s66, v152
	v_mul_f32_e32 v153, s66, v153
	v_add_u32_e32 v156, 0x2c000, v154
	v_cvt_pk_bf16_f32 v206, v146, v147
	v_cvt_pk_bf16_f32 v207, v148, v149
	v_cvt_pk_bf16_f32 v208, v150, v151
	v_cvt_pk_bf16_f32 v209, v152, v153
	global_store_dwordx4 v156, v[206:209], s[24:25]
	v_mul_f32_e32 v146, v4, v195
	v_mul_f32_e32 v147, v5, v195
	v_mul_f32_e32 v148, v6, v195
	v_mul_f32_e32 v149, v7, v195
	v_mul_f32_e32 v150, v0, v195
	v_mul_f32_e32 v151, v1, v195
	v_mul_f32_e32 v152, v2, v195
	v_mul_f32_e32 v153, v3, v195
	v_mul_f32_e32 v146, s66, v146
	v_mul_f32_e32 v147, s66, v147
	v_mul_f32_e32 v148, s66, v148
	v_mul_f32_e32 v149, s66, v149
	v_mul_f32_e32 v150, s66, v150
	v_mul_f32_e32 v151, s66, v151
	v_mul_f32_e32 v152, s66, v152
	v_mul_f32_e32 v153, s66, v153
	v_add_u32_e32 v156, 0x2c100, v154
	v_cvt_pk_bf16_f32 v210, v146, v147
	v_cvt_pk_bf16_f32 v211, v148, v149
	v_cvt_pk_bf16_f32 v212, v150, v151
	v_cvt_pk_bf16_f32 v213, v152, v153
	global_store_dwordx4 v156, v[210:213], s[24:25]
	s_mov_b64 s[22:23], exec
	s_branch .LBB0_639
.Lepf_gates:
	v_readlane_b32 s24, v250, 38
	v_readlane_b32 s25, v250, 39
	s_add_i32 s23, s97, -9
	s_lshl_b32 s23, s23, 8
	s_lshl_b32 s22, s23, 1
	s_waitcnt lgkmcnt(0)
	v_lshlrev_b32_e32 v154, 12, v192
	v_lshl_add_u32 v154, v166, 1, v154
	v_add_u32_e32 v154, s22, v154
	v_add_u32_e32 v155, s23, v166
	v_lshlrev_b32_e32 v155, 2, v155
	v_add_u32_e32 v155, 0x23040, v155
	ds_read_b128 v[130:133], v155
	ds_read_b128 v[134:137], v155 offset:16
	ds_read_b128 v[138:141], v155 offset:512
	ds_read_b128 v[142:145], v155 offset:528
	s_waitcnt lgkmcnt(0)
; #define LAS __attribute__((address_space(3)))
; DI unsigned pk2(float lo, float hi) { f32x2 v = {lo, hi}; hbf2 r = __builtin_convertvector(v, hbf2); return __builtin_bit_cast(unsigned, r); }
; DI float sigmoidf_(float a) { return fast_rcp(1.0f + fast_exp2(-a * LOG2E)); }
;     DI void operator()(f32x4 (&acc)[2][2][4][2], const Unit& u, int wr, int wc, int fr, int fq, LAS unsigned char* lds) const {
;     ...
;                     else { dst = GATES; ld = 2048; c0 = gcol - 2304;
;                         const f32x4 g0 = *(const LAS f32x4*)(lds + BG_OFF + (c0 + cw) * 4), g1 = *(const LAS f32x4*)(lds + BG_OFF + (c0 + cw + 4) * 4);
; #pragma unroll
;                         for (int j = 0; j < 4; ++j) { v0[j] = sigmoidf_(v0[j] + g0[j]); v1[j] = sigmoidf_(v1[j] + g1[j]); } }
;                     u32x4 w; w.x = pk2(v0[0], v0[1]); w.y = pk2(v0[2], v0[3]); w.z = pk2(v1[0], v1[1]); w.w = pk2(v1[2], v1[3]);
;                     *(u32x4*)(dst + (size_t)row * ld + c0 + cw) = w;
	v_mul_f32_e32 v146, v126, v220
	v_mul_f32_e32 v147, v127, v220
	v_mul_f32_e32 v148, v128, v220
	v_mul_f32_e32 v149, v129, v220
	v_mul_f32_e32 v150, v122, v220
	v_mul_f32_e32 v151, v123, v220
	v_mul_f32_e32 v152, v124, v220
	v_mul_f32_e32 v153, v125, v220
	v_add_f32_e32 v146, v146, v130
	v_add_f32_e32 v147, v147, v131
	v_add_f32_e32 v148, v148, v132
	v_add_f32_e32 v149, v149, v133
	v_add_f32_e32 v150, v150, v134
	v_add_f32_e32 v151, v151, v135
	v_add_f32_e32 v152, v152, v136
	v_add_f32_e32 v153, v153, v137
	v_mul_f32_e32 v146, 0xbfb8aa3b, v146
	v_mul_f32_e32 v147, 0xbfb8aa3b, v147
	v_mul_f32_e32 v148, 0xbfb8aa3b, v148
	v_mul_f32_e32 v149, 0xbfb8aa3b, v149
	v_mul_f32_e32 v150, 0xbfb8aa3b, v150
	v_mul_f32_e32 v151, 0xbfb8aa3b, v151
	v_mul_f32_e32 v152, 0xbfb8aa3b, v152
	v_mul_f32_e32 v153, 0xbfb8aa3b, v153
	v_exp_f32_e32 v146, v146
	v_exp_f32_e32 v147, v147
	v_exp_f32_e32 v148, v148
	v_exp_f32_e32 v149, v149
	v_exp_f32_e32 v150, v150
	v_exp_f32_e32 v151, v151
	v_exp_f32_e32 v152, v152
	v_exp_f32_e32 v153, v153
	v_add_f32_e32 v146, 1.0, v146
	v_add_f32_e32 v147, 1.0, v147
	v_add_f32_e32 v148, 1.0, v148
	v_add_f32_e32 v149, 1.0, v149
	v_add_f32_e32 v150, 1.0, v150
	v_add_f32_e32 v151, 1.0, v151
	v_add_f32_e32 v152, 1.0, v152
	v_add_f32_e32 v153, 1.0, v153
	v_rcp_f32_e32 v146, v146
	v_rcp_f32_e32 v147, v147
	v_rcp_f32_e32 v148, v148
	v_rcp_f32_e32 v149, v149
	v_rcp_f32_e32 v150, v150
	v_rcp_f32_e32 v151, v151
	v_rcp_f32_e32 v152, v152
	v_rcp_f32_e32 v153, v153
	v_add_u32_e32 v156, 0x0, v154
	v_cvt_pk_bf16_f32 v206, v146, v147
	v_cvt_pk_bf16_f32 v207, v148, v149
	v_cvt_pk_bf16_f32 v208, v150, v151
	v_cvt_pk_bf16_f32 v209, v152, v153
	global_store_dwordx4 v156, v[206:209], s[24:25]
	v_mul_f32_e32 v146, v92, v220
	v_mul_f32_e32 v147, v93, v220
	v_mul_f32_e32 v148, v94, v220
	v_mul_f32_e32 v149, v95, v220
	v_mul_f32_e32 v150, v88, v220
	v_mul_f32_e32 v151, v89, v220
	v_mul_f32_e32 v152, v90, v220
	v_mul_f32_e32 v153, v91, v220
	v_add_f32_e32 v146, v146, v138
	v_add_f32_e32 v147, v147, v139
	v_add_f32_e32 v148, v148, v140
	v_add_f32_e32 v149, v149, v141
	v_add_f32_e32 v150, v150, v142
	v_add_f32_e32 v151, v151, v143
	v_add_f32_e32 v152, v152, v144
	v_add_f32_e32 v153, v153, v145
	v_mul_f32_e32 v146, 0xbfb8aa3b, v146
	v_mul_f32_e32 v147, 0xbfb8aa3b, v147
	v_mul_f32_e32 v148, 0xbfb8aa3b, v148
	v_mul_f32_e32 v149, 0xbfb8aa3b, v149
	v_mul_f32_e32 v150, 0xbfb8aa3b, v150
	v_mul_f32_e32 v151, 0xbfb8aa3b, v151
	v_mul_f32_e32 v152, 0xbfb8aa3b, v152
	v_mul_f32_e32 v153, 0xbfb8aa3b, v153
	v_exp_f32_e32 v146, v146
	v_exp_f32_e32 v147, v147
	v_exp_f32_e32 v148, v148
	v_exp_f32_e32 v149, v149
	v_exp_f32_e32 v150, v150
	v_exp_f32_e32 v151, v151
	v_exp_f32_e32 v152, v152
	v_exp_f32_e32 v153, v153
	v_add_f32_e32 v146, 1.0, v146
	v_add_f32_e32 v147, 1.0, v147
	v_add_f32_e32 v148, 1.0, v148
	v_add_f32_e32 v149, 1.0, v149
	v_add_f32_e32 v150, 1.0, v150
	v_add_f32_e32 v151, 1.0, v151
	v_add_f32_e32 v152, 1.0, v152
	v_add_f32_e32 v153, 1.0, v153
	v_rcp_f32_e32 v146, v146
	v_rcp_f32_e32 v147, v147
	v_rcp_f32_e32 v148, v148
	v_rcp_f32_e32 v149, v149
	v_rcp_f32_e32 v150, v150
	v_rcp_f32_e32 v151, v151
	v_rcp_f32_e32 v152, v152
	v_rcp_f32_e32 v153, v153
	v_add_u32_e32 v156, 0x100, v154
	v_cvt_pk_bf16_f32 v210, v146, v147
	v_cvt_pk_bf16_f32 v211, v148, v149
	v_cvt_pk_bf16_f32 v212, v150, v151
	v_cvt_pk_bf16_f32 v213, v152, v153
	global_store_dwordx4 v156, v[210:213], s[24:25]
	v_mul_f32_e32 v146, v118, v221
	v_mul_f32_e32 v147, v119, v221
	v_mul_f32_e32 v148, v120, v221
	v_mul_f32_e32 v149, v121, v221
	v_mul_f32_e32 v150, v114, v221
	v_mul_f32_e32 v151, v115, v221
	v_mul_f32_e32 v152, v116, v221
	v_mul_f32_e32 v153, v117, v221
	v_add_f32_e32 v146, v146, v130
	v_add_f32_e32 v147, v147, v131
	v_add_f32_e32 v148, v148, v132
	v_add_f32_e32 v149, v149, v133
	v_add_f32_e32 v150, v150, v134
	v_add_f32_e32 v151, v151, v135
	v_add_f32_e32 v152, v152, v136
	v_add_f32_e32 v153, v153, v137
	v_mul_f32_e32 v146, 0xbfb8aa3b, v146
	v_mul_f32_e32 v147, 0xbfb8aa3b, v147
	v_mul_f32_e32 v148, 0xbfb8aa3b, v148
	v_mul_f32_e32 v149, 0xbfb8aa3b, v149
	v_mul_f32_e32 v150, 0xbfb8aa3b, v150
	v_mul_f32_e32 v151, 0xbfb8aa3b, v151
	v_mul_f32_e32 v152, 0xbfb8aa3b, v152
	v_mul_f32_e32 v153, 0xbfb8aa3b, v153
	v_exp_f32_e32 v146, v146
	v_exp_f32_e32 v147, v147
	v_exp_f32_e32 v148, v148
	v_exp_f32_e32 v149, v149
	v_exp_f32_e32 v150, v150
	v_exp_f32_e32 v151, v151
	v_exp_f32_e32 v152, v152
	v_exp_f32_e32 v153, v153
	v_add_f32_e32 v146, 1.0, v146
	v_add_f32_e32 v147, 1.0, v147
	v_add_f32_e32 v148, 1.0, v148
	v_add_f32_e32 v149, 1.0, v149
	v_add_f32_e32 v150, 1.0, v150
	v_add_f32_e32 v151, 1.0, v151
	v_add_f32_e32 v152, 1.0, v152
	v_add_f32_e32 v153, 1.0, v153
	v_rcp_f32_e32 v146, v146
	v_rcp_f32_e32 v147, v147
	v_rcp_f32_e32 v148, v148
	v_rcp_f32_e32 v149, v149
	v_rcp_f32_e32 v150, v150
	v_rcp_f32_e32 v151, v151
	v_rcp_f32_e32 v152, v152
	v_rcp_f32_e32 v153, v153
	v_add_u32_e32 v156, 0x10000, v154
	v_cvt_pk_bf16_f32 v206, v146, v147
	v_cvt_pk_bf16_f32 v207, v148, v149
	v_cvt_pk_bf16_f32 v208, v150, v151
	v_cvt_pk_bf16_f32 v209, v152, v153
	global_store_dwordx4 v156, v[206:209], s[24:25]
	v_mul_f32_e32 v146, v84, v221
	v_mul_f32_e32 v147, v85, v221
	v_mul_f32_e32 v148, v86, v221
	v_mul_f32_e32 v149, v87, v221
	v_mul_f32_e32 v150, v80, v221
	v_mul_f32_e32 v151, v81, v221
	v_mul_f32_e32 v152, v82, v221
	v_mul_f32_e32 v153, v83, v221
	v_add_f32_e32 v146, v146, v138
	v_add_f32_e32 v147, v147, v139
	v_add_f32_e32 v148, v148, v140
	v_add_f32_e32 v149, v149, v141
	v_add_f32_e32 v150, v150, v142
	v_add_f32_e32 v151, v151, v143
	v_add_f32_e32 v152, v152, v144
	v_add_f32_e32 v153, v153, v145
	v_mul_f32_e32 v146, 0xbfb8aa3b, v146
; #define LAS __attribute__((address_space(3)))
; DI unsigned pk2(float lo, float hi) { f32x2 v = {lo, hi}; hbf2 r = __builtin_convertvector(v, hbf2); return __builtin_bit_cast(unsigned, r); }
; DI float sigmoidf_(float a) { return fast_rcp(1.0f + fast_exp2(-a * LOG2E)); }
;     DI void operator()(f32x4 (&acc)[2][2][4][2], const Unit& u, int wr, int wc, int fr, int fq, LAS unsigned char* lds) const {
;     ...
;                     else { dst = GATES; ld = 2048; c0 = gcol - 2304;
;                         const f32x4 g0 = *(const LAS f32x4*)(lds + BG_OFF + (c0 + cw) * 4), g1 = *(const LAS f32x4*)(lds + BG_OFF + (c0 + cw + 4) * 4);
; #pragma unroll
;                         for (int j = 0; j < 4; ++j) { v0[j] = sigmoidf_(v0[j] + g0[j]); v1[j] = sigmoidf_(v1[j] + g1[j]); } }
;                     u32x4 w; w.x = pk2(v0[0], v0[1]); w.y = pk2(v0[2], v0[3]); w.z = pk2(v1[0], v1[1]); w.w = pk2(v1[2], v1[3]);
;                     *(u32x4*)(dst + (size_t)row * ld + c0 + cw) = w;
	v_mul_f32_e32 v147, 0xbfb8aa3b, v147
	v_mul_f32_e32 v148, 0xbfb8aa3b, v148
	v_mul_f32_e32 v149, 0xbfb8aa3b, v149
	v_mul_f32_e32 v150, 0xbfb8aa3b, v150
	v_mul_f32_e32 v151, 0xbfb8aa3b, v151
	v_mul_f32_e32 v152, 0xbfb8aa3b, v152
	v_mul_f32_e32 v153, 0xbfb8aa3b, v153
	v_exp_f32_e32 v146, v146
	v_exp_f32_e32 v147, v147
	v_exp_f32_e32 v148, v148
	v_exp_f32_e32 v149, v149
	v_exp_f32_e32 v150, v150
	v_exp_f32_e32 v151, v151
	v_exp_f32_e32 v152, v152
	v_exp_f32_e32 v153, v153
	v_add_f32_e32 v146, 1.0, v146
	v_add_f32_e32 v147, 1.0, v147
	v_add_f32_e32 v148, 1.0, v148
	v_add_f32_e32 v149, 1.0, v149
	v_add_f32_e32 v150, 1.0, v150
	v_add_f32_e32 v151, 1.0, v151
	v_add_f32_e32 v152, 1.0, v152
	v_add_f32_e32 v153, 1.0, v153
	v_rcp_f32_e32 v146, v146
	v_rcp_f32_e32 v147, v147
	v_rcp_f32_e32 v148, v148
	v_rcp_f32_e32 v149, v149
	v_rcp_f32_e32 v150, v150
	v_rcp_f32_e32 v151, v151
	v_rcp_f32_e32 v152, v152
	v_rcp_f32_e32 v153, v153
	v_add_u32_e32 v156, 0x10100, v154
	v_cvt_pk_bf16_f32 v210, v146, v147
	v_cvt_pk_bf16_f32 v211, v148, v149
	v_cvt_pk_bf16_f32 v212, v150, v151
	v_cvt_pk_bf16_f32 v213, v152, v153
	global_store_dwordx4 v156, v[210:213], s[24:25]
	v_mul_f32_e32 v146, v110, v204
	v_mul_f32_e32 v147, v111, v204
	v_mul_f32_e32 v148, v112, v204
	v_mul_f32_e32 v149, v113, v204
	v_mul_f32_e32 v150, v106, v204
	v_mul_f32_e32 v151, v107, v204
	v_mul_f32_e32 v152, v108, v204
	v_mul_f32_e32 v153, v109, v204
	v_add_f32_e32 v146, v146, v130
	v_add_f32_e32 v147, v147, v131
	v_add_f32_e32 v148, v148, v132
	v_add_f32_e32 v149, v149, v133
	v_add_f32_e32 v150, v150, v134
	v_add_f32_e32 v151, v151, v135
	v_add_f32_e32 v152, v152, v136
	v_add_f32_e32 v153, v153, v137
	v_mul_f32_e32 v146, 0xbfb8aa3b, v146
	v_mul_f32_e32 v147, 0xbfb8aa3b, v147
	v_mul_f32_e32 v148, 0xbfb8aa3b, v148
	v_mul_f32_e32 v149, 0xbfb8aa3b, v149
	v_mul_f32_e32 v150, 0xbfb8aa3b, v150
	v_mul_f32_e32 v151, 0xbfb8aa3b, v151
	v_mul_f32_e32 v152, 0xbfb8aa3b, v152
	v_mul_f32_e32 v153, 0xbfb8aa3b, v153
	v_exp_f32_e32 v146, v146
	v_exp_f32_e32 v147, v147
	v_exp_f32_e32 v148, v148
	v_exp_f32_e32 v149, v149
	v_exp_f32_e32 v150, v150
	v_exp_f32_e32 v151, v151
	v_exp_f32_e32 v152, v152
	v_exp_f32_e32 v153, v153
	v_add_f32_e32 v146, 1.0, v146
	v_add_f32_e32 v147, 1.0, v147
	v_add_f32_e32 v148, 1.0, v148
	v_add_f32_e32 v149, 1.0, v149
	v_add_f32_e32 v150, 1.0, v150
	v_add_f32_e32 v151, 1.0, v151
	v_add_f32_e32 v152, 1.0, v152
	v_add_f32_e32 v153, 1.0, v153
	v_rcp_f32_e32 v146, v146
	v_rcp_f32_e32 v147, v147
	v_rcp_f32_e32 v148, v148
	v_rcp_f32_e32 v149, v149
	v_rcp_f32_e32 v150, v150
	v_rcp_f32_e32 v151, v151
	v_rcp_f32_e32 v152, v152
	v_rcp_f32_e32 v153, v153
	v_add_u32_e32 v156, 0x20000, v154
	v_cvt_pk_bf16_f32 v206, v146, v147
	v_cvt_pk_bf16_f32 v207, v148, v149
	v_cvt_pk_bf16_f32 v208, v150, v151
	v_cvt_pk_bf16_f32 v209, v152, v153
	global_store_dwordx4 v156, v[206:209], s[24:25]
	v_mul_f32_e32 v146, v76, v204
	v_mul_f32_e32 v147, v77, v204
	v_mul_f32_e32 v148, v78, v204
	v_mul_f32_e32 v149, v79, v204
	v_mul_f32_e32 v150, v72, v204
	v_mul_f32_e32 v151, v73, v204
	v_mul_f32_e32 v152, v74, v204
	v_mul_f32_e32 v153, v75, v204
	v_add_f32_e32 v146, v146, v138
	v_add_f32_e32 v147, v147, v139
	v_add_f32_e32 v148, v148, v140
	v_add_f32_e32 v149, v149, v141
	v_add_f32_e32 v150, v150, v142
	v_add_f32_e32 v151, v151, v143
	v_add_f32_e32 v152, v152, v144
	v_add_f32_e32 v153, v153, v145
	v_mul_f32_e32 v146, 0xbfb8aa3b, v146
	v_mul_f32_e32 v147, 0xbfb8aa3b, v147
	v_mul_f32_e32 v148, 0xbfb8aa3b, v148
	v_mul_f32_e32 v149, 0xbfb8aa3b, v149
	v_mul_f32_e32 v150, 0xbfb8aa3b, v150
	v_mul_f32_e32 v151, 0xbfb8aa3b, v151
	v_mul_f32_e32 v152, 0xbfb8aa3b, v152
	v_mul_f32_e32 v153, 0xbfb8aa3b, v153
	v_exp_f32_e32 v146, v146
	v_exp_f32_e32 v147, v147
	v_exp_f32_e32 v148, v148
	v_exp_f32_e32 v149, v149
	v_exp_f32_e32 v150, v150
	v_exp_f32_e32 v151, v151
	v_exp_f32_e32 v152, v152
	v_exp_f32_e32 v153, v153
	v_add_f32_e32 v146, 1.0, v146
	v_add_f32_e32 v147, 1.0, v147
	v_add_f32_e32 v148, 1.0, v148
	v_add_f32_e32 v149, 1.0, v149
	v_add_f32_e32 v150, 1.0, v150
	v_add_f32_e32 v151, 1.0, v151
	v_add_f32_e32 v152, 1.0, v152
	v_add_f32_e32 v153, 1.0, v153
	v_rcp_f32_e32 v146, v146
	v_rcp_f32_e32 v147, v147
	v_rcp_f32_e32 v148, v148
	v_rcp_f32_e32 v149, v149
	v_rcp_f32_e32 v150, v150
	v_rcp_f32_e32 v151, v151
	v_rcp_f32_e32 v152, v152
	v_rcp_f32_e32 v153, v153
	v_add_u32_e32 v156, 0x20100, v154
	v_cvt_pk_bf16_f32 v210, v146, v147
	v_cvt_pk_bf16_f32 v211, v148, v149
	v_cvt_pk_bf16_f32 v212, v150, v151
	v_cvt_pk_bf16_f32 v213, v152, v153
	global_store_dwordx4 v156, v[210:213], s[24:25]
	v_mul_f32_e32 v146, v102, v205
	v_mul_f32_e32 v147, v103, v205
	v_mul_f32_e32 v148, v104, v205
	v_mul_f32_e32 v149, v105, v205
	v_mul_f32_e32 v150, v98, v205
	v_mul_f32_e32 v151, v99, v205
	v_mul_f32_e32 v152, v100, v205
	v_mul_f32_e32 v153, v101, v205
	v_add_f32_e32 v146, v146, v130
	v_add_f32_e32 v147, v147, v131
	v_add_f32_e32 v148, v148, v132
	v_add_f32_e32 v149, v149, v133
	v_add_f32_e32 v150, v150, v134
	v_add_f32_e32 v151, v151, v135
	v_add_f32_e32 v152, v152, v136
	v_add_f32_e32 v153, v153, v137
	v_mul_f32_e32 v146, 0xbfb8aa3b, v146
	v_mul_f32_e32 v147, 0xbfb8aa3b, v147
	v_mul_f32_e32 v148, 0xbfb8aa3b, v148
	v_mul_f32_e32 v149, 0xbfb8aa3b, v149
	v_mul_f32_e32 v150, 0xbfb8aa3b, v150
	v_mul_f32_e32 v151, 0xbfb8aa3b, v151
	v_mul_f32_e32 v152, 0xbfb8aa3b, v152
	v_mul_f32_e32 v153, 0xbfb8aa3b, v153
	v_exp_f32_e32 v146, v146
	v_exp_f32_e32 v147, v147
	v_exp_f32_e32 v148, v148
	v_exp_f32_e32 v149, v149
	v_exp_f32_e32 v150, v150
	v_exp_f32_e32 v151, v151
	v_exp_f32_e32 v152, v152
	v_exp_f32_e32 v153, v153
	v_add_f32_e32 v146, 1.0, v146
	v_add_f32_e32 v147, 1.0, v147
; #define LAS __attribute__((address_space(3)))
; DI unsigned pk2(float lo, float hi) { f32x2 v = {lo, hi}; hbf2 r = __builtin_convertvector(v, hbf2); return __builtin_bit_cast(unsigned, r); }
; DI float sigmoidf_(float a) { return fast_rcp(1.0f + fast_exp2(-a * LOG2E)); }
;     DI void operator()(f32x4 (&acc)[2][2][4][2], const Unit& u, int wr, int wc, int fr, int fq, LAS unsigned char* lds) const {
;     ...
;                     else { dst = GATES; ld = 2048; c0 = gcol - 2304;
;                         const f32x4 g0 = *(const LAS f32x4*)(lds + BG_OFF + (c0 + cw) * 4), g1 = *(const LAS f32x4*)(lds + BG_OFF + (c0 + cw + 4) * 4);
; #pragma unroll
;                         for (int j = 0; j < 4; ++j) { v0[j] = sigmoidf_(v0[j] + g0[j]); v1[j] = sigmoidf_(v1[j] + g1[j]); } }
;                     u32x4 w; w.x = pk2(v0[0], v0[1]); w.y = pk2(v0[2], v0[3]); w.z = pk2(v1[0], v1[1]); w.w = pk2(v1[2], v1[3]);
;                     *(u32x4*)(dst + (size_t)row * ld + c0 + cw) = w;
	v_add_f32_e32 v148, 1.0, v148
	v_add_f32_e32 v149, 1.0, v149
	v_add_f32_e32 v150, 1.0, v150
	v_add_f32_e32 v151, 1.0, v151
	v_add_f32_e32 v152, 1.0, v152
	v_add_f32_e32 v153, 1.0, v153
	v_rcp_f32_e32 v146, v146
	v_rcp_f32_e32 v147, v147
	v_rcp_f32_e32 v148, v148
	v_rcp_f32_e32 v149, v149
	v_rcp_f32_e32 v150, v150
	v_rcp_f32_e32 v151, v151
	v_rcp_f32_e32 v152, v152
	v_rcp_f32_e32 v153, v153
	v_add_u32_e32 v156, 0x30000, v154
	v_cvt_pk_bf16_f32 v206, v146, v147
	v_cvt_pk_bf16_f32 v207, v148, v149
	v_cvt_pk_bf16_f32 v208, v150, v151
	v_cvt_pk_bf16_f32 v209, v152, v153
	global_store_dwordx4 v156, v[206:209], s[24:25]
	v_mul_f32_e32 v146, v68, v205
	v_mul_f32_e32 v147, v69, v205
	v_mul_f32_e32 v148, v70, v205
	v_mul_f32_e32 v149, v71, v205
	v_mul_f32_e32 v150, v64, v205
	v_mul_f32_e32 v151, v65, v205
	v_mul_f32_e32 v152, v66, v205
	v_mul_f32_e32 v153, v67, v205
	v_add_f32_e32 v146, v146, v138
	v_add_f32_e32 v147, v147, v139
	v_add_f32_e32 v148, v148, v140
	v_add_f32_e32 v149, v149, v141
	v_add_f32_e32 v150, v150, v142
	v_add_f32_e32 v151, v151, v143
	v_add_f32_e32 v152, v152, v144
	v_add_f32_e32 v153, v153, v145
	v_mul_f32_e32 v146, 0xbfb8aa3b, v146
	v_mul_f32_e32 v147, 0xbfb8aa3b, v147
	v_mul_f32_e32 v148, 0xbfb8aa3b, v148
	v_mul_f32_e32 v149, 0xbfb8aa3b, v149
	v_mul_f32_e32 v150, 0xbfb8aa3b, v150
	v_mul_f32_e32 v151, 0xbfb8aa3b, v151
	v_mul_f32_e32 v152, 0xbfb8aa3b, v152
	v_mul_f32_e32 v153, 0xbfb8aa3b, v153
	v_exp_f32_e32 v146, v146
	v_exp_f32_e32 v147, v147
	v_exp_f32_e32 v148, v148
	v_exp_f32_e32 v149, v149
	v_exp_f32_e32 v150, v150
	v_exp_f32_e32 v151, v151
	v_exp_f32_e32 v152, v152
	v_exp_f32_e32 v153, v153
	v_add_f32_e32 v146, 1.0, v146
	v_add_f32_e32 v147, 1.0, v147
	v_add_f32_e32 v148, 1.0, v148
	v_add_f32_e32 v149, 1.0, v149
	v_add_f32_e32 v150, 1.0, v150
	v_add_f32_e32 v151, 1.0, v151
	v_add_f32_e32 v152, 1.0, v152
	v_add_f32_e32 v153, 1.0, v153
	v_rcp_f32_e32 v146, v146
	v_rcp_f32_e32 v147, v147
	v_rcp_f32_e32 v148, v148
	v_rcp_f32_e32 v149, v149
	v_rcp_f32_e32 v150, v150
	v_rcp_f32_e32 v151, v151
	v_rcp_f32_e32 v152, v152
	v_rcp_f32_e32 v153, v153
	v_add_u32_e32 v156, 0x30100, v154
	v_cvt_pk_bf16_f32 v210, v146, v147
	v_cvt_pk_bf16_f32 v211, v148, v149
	v_cvt_pk_bf16_f32 v212, v150, v151
	v_cvt_pk_bf16_f32 v213, v152, v153
	global_store_dwordx4 v156, v[210:213], s[24:25]
	v_mul_f32_e32 v146, v60, v198
	v_mul_f32_e32 v147, v61, v198
	v_mul_f32_e32 v148, v62, v198
	v_mul_f32_e32 v149, v63, v198
	v_mul_f32_e32 v150, v56, v198
	v_mul_f32_e32 v151, v57, v198
	v_mul_f32_e32 v152, v58, v198
	v_mul_f32_e32 v153, v59, v198
	v_add_f32_e32 v146, v146, v130
	v_add_f32_e32 v147, v147, v131
	v_add_f32_e32 v148, v148, v132
	v_add_f32_e32 v149, v149, v133
	v_add_f32_e32 v150, v150, v134
	v_add_f32_e32 v151, v151, v135
	v_add_f32_e32 v152, v152, v136
	v_add_f32_e32 v153, v153, v137
	v_mul_f32_e32 v146, 0xbfb8aa3b, v146
	v_mul_f32_e32 v147, 0xbfb8aa3b, v147
	v_mul_f32_e32 v148, 0xbfb8aa3b, v148
	v_mul_f32_e32 v149, 0xbfb8aa3b, v149
	v_mul_f32_e32 v150, 0xbfb8aa3b, v150
	v_mul_f32_e32 v151, 0xbfb8aa3b, v151
	v_mul_f32_e32 v152, 0xbfb8aa3b, v152
	v_mul_f32_e32 v153, 0xbfb8aa3b, v153
	v_exp_f32_e32 v146, v146
	v_exp_f32_e32 v147, v147
	v_exp_f32_e32 v148, v148
	v_exp_f32_e32 v149, v149
	v_exp_f32_e32 v150, v150
	v_exp_f32_e32 v151, v151
	v_exp_f32_e32 v152, v152
	v_exp_f32_e32 v153, v153
	v_add_f32_e32 v146, 1.0, v146
	v_add_f32_e32 v147, 1.0, v147
	v_add_f32_e32 v148, 1.0, v148
	v_add_f32_e32 v149, 1.0, v149
	v_add_f32_e32 v150, 1.0, v150
	v_add_f32_e32 v151, 1.0, v151
	v_add_f32_e32 v152, 1.0, v152
	v_add_f32_e32 v153, 1.0, v153
	v_rcp_f32_e32 v146, v146
	v_rcp_f32_e32 v147, v147
	v_rcp_f32_e32 v148, v148
	v_rcp_f32_e32 v149, v149
	v_rcp_f32_e32 v150, v150
	v_rcp_f32_e32 v151, v151
	v_rcp_f32_e32 v152, v152
	v_rcp_f32_e32 v153, v153
	v_add_u32_e32 v156, 0x80000, v154
	v_cvt_pk_bf16_f32 v206, v146, v147
	v_cvt_pk_bf16_f32 v207, v148, v149
	v_cvt_pk_bf16_f32 v208, v150, v151
	v_cvt_pk_bf16_f32 v209, v152, v153
	global_store_dwordx4 v156, v[206:209], s[24:25]
	v_mul_f32_e32 v146, v28, v198
	v_mul_f32_e32 v147, v29, v198
	v_mul_f32_e32 v148, v30, v198
	v_mul_f32_e32 v149, v31, v198
	v_mul_f32_e32 v150, v24, v198
	v_mul_f32_e32 v151, v25, v198
	v_mul_f32_e32 v152, v26, v198
	v_mul_f32_e32 v153, v27, v198
	v_add_f32_e32 v146, v146, v138
	v_add_f32_e32 v147, v147, v139
	v_add_f32_e32 v148, v148, v140
	v_add_f32_e32 v149, v149, v141
	v_add_f32_e32 v150, v150, v142
	v_add_f32_e32 v151, v151, v143
	v_add_f32_e32 v152, v152, v144
	v_add_f32_e32 v153, v153, v145
	v_mul_f32_e32 v146, 0xbfb8aa3b, v146
	v_mul_f32_e32 v147, 0xbfb8aa3b, v147
	v_mul_f32_e32 v148, 0xbfb8aa3b, v148
	v_mul_f32_e32 v149, 0xbfb8aa3b, v149
	v_mul_f32_e32 v150, 0xbfb8aa3b, v150
	v_mul_f32_e32 v151, 0xbfb8aa3b, v151
	v_mul_f32_e32 v152, 0xbfb8aa3b, v152
	v_mul_f32_e32 v153, 0xbfb8aa3b, v153
	v_exp_f32_e32 v146, v146
	v_exp_f32_e32 v147, v147
	v_exp_f32_e32 v148, v148
	v_exp_f32_e32 v149, v149
	v_exp_f32_e32 v150, v150
	v_exp_f32_e32 v151, v151
	v_exp_f32_e32 v152, v152
	v_exp_f32_e32 v153, v153
	v_add_f32_e32 v146, 1.0, v146
	v_add_f32_e32 v147, 1.0, v147
	v_add_f32_e32 v148, 1.0, v148
	v_add_f32_e32 v149, 1.0, v149
	v_add_f32_e32 v150, 1.0, v150
	v_add_f32_e32 v151, 1.0, v151
	v_add_f32_e32 v152, 1.0, v152
	v_add_f32_e32 v153, 1.0, v153
	v_rcp_f32_e32 v146, v146
	v_rcp_f32_e32 v147, v147
	v_rcp_f32_e32 v148, v148
	v_rcp_f32_e32 v149, v149
	v_rcp_f32_e32 v150, v150
	v_rcp_f32_e32 v151, v151
	v_rcp_f32_e32 v152, v152
	v_rcp_f32_e32 v153, v153
	v_add_u32_e32 v156, 0x80100, v154
	v_cvt_pk_bf16_f32 v210, v146, v147
	v_cvt_pk_bf16_f32 v211, v148, v149
	v_cvt_pk_bf16_f32 v212, v150, v151
; #define LAS __attribute__((address_space(3)))
; DI unsigned pk2(float lo, float hi) { f32x2 v = {lo, hi}; hbf2 r = __builtin_convertvector(v, hbf2); return __builtin_bit_cast(unsigned, r); }
; DI float sigmoidf_(float a) { return fast_rcp(1.0f + fast_exp2(-a * LOG2E)); }
;     DI void operator()(f32x4 (&acc)[2][2][4][2], const Unit& u, int wr, int wc, int fr, int fq, LAS unsigned char* lds) const {
;     ...
;                     else { dst = GATES; ld = 2048; c0 = gcol - 2304;
;                         const f32x4 g0 = *(const LAS f32x4*)(lds + BG_OFF + (c0 + cw) * 4), g1 = *(const LAS f32x4*)(lds + BG_OFF + (c0 + cw + 4) * 4);
; #pragma unroll
;                         for (int j = 0; j < 4; ++j) { v0[j] = sigmoidf_(v0[j] + g0[j]); v1[j] = sigmoidf_(v1[j] + g1[j]); } }
;                     u32x4 w; w.x = pk2(v0[0], v0[1]); w.y = pk2(v0[2], v0[3]); w.z = pk2(v1[0], v1[1]); w.w = pk2(v1[2], v1[3]);
;                     *(u32x4*)(dst + (size_t)row * ld + c0 + cw) = w;
	v_cvt_pk_bf16_f32 v213, v152, v153
	global_store_dwordx4 v156, v[210:213], s[24:25]
	v_mul_f32_e32 v146, v52, v199
	v_mul_f32_e32 v147, v53, v199
	v_mul_f32_e32 v148, v54, v199
	v_mul_f32_e32 v149, v55, v199
	v_mul_f32_e32 v150, v48, v199
	v_mul_f32_e32 v151, v49, v199
	v_mul_f32_e32 v152, v50, v199
	v_mul_f32_e32 v153, v51, v199
	v_add_f32_e32 v146, v146, v130
	v_add_f32_e32 v147, v147, v131
	v_add_f32_e32 v148, v148, v132
	v_add_f32_e32 v149, v149, v133
	v_add_f32_e32 v150, v150, v134
	v_add_f32_e32 v151, v151, v135
	v_add_f32_e32 v152, v152, v136
	v_add_f32_e32 v153, v153, v137
	v_mul_f32_e32 v146, 0xbfb8aa3b, v146
	v_mul_f32_e32 v147, 0xbfb8aa3b, v147
	v_mul_f32_e32 v148, 0xbfb8aa3b, v148
	v_mul_f32_e32 v149, 0xbfb8aa3b, v149
	v_mul_f32_e32 v150, 0xbfb8aa3b, v150
	v_mul_f32_e32 v151, 0xbfb8aa3b, v151
	v_mul_f32_e32 v152, 0xbfb8aa3b, v152
	v_mul_f32_e32 v153, 0xbfb8aa3b, v153
	v_exp_f32_e32 v146, v146
	v_exp_f32_e32 v147, v147
	v_exp_f32_e32 v148, v148
	v_exp_f32_e32 v149, v149
	v_exp_f32_e32 v150, v150
	v_exp_f32_e32 v151, v151
	v_exp_f32_e32 v152, v152
	v_exp_f32_e32 v153, v153
	v_add_f32_e32 v146, 1.0, v146
	v_add_f32_e32 v147, 1.0, v147
	v_add_f32_e32 v148, 1.0, v148
	v_add_f32_e32 v149, 1.0, v149
	v_add_f32_e32 v150, 1.0, v150
	v_add_f32_e32 v151, 1.0, v151
	v_add_f32_e32 v152, 1.0, v152
	v_add_f32_e32 v153, 1.0, v153
	v_rcp_f32_e32 v146, v146
	v_rcp_f32_e32 v147, v147
	v_rcp_f32_e32 v148, v148
	v_rcp_f32_e32 v149, v149
	v_rcp_f32_e32 v150, v150
	v_rcp_f32_e32 v151, v151
	v_rcp_f32_e32 v152, v152
	v_rcp_f32_e32 v153, v153
	v_add_u32_e32 v156, 0x90000, v154
	v_cvt_pk_bf16_f32 v206, v146, v147
	v_cvt_pk_bf16_f32 v207, v148, v149
	v_cvt_pk_bf16_f32 v208, v150, v151
	v_cvt_pk_bf16_f32 v209, v152, v153
	global_store_dwordx4 v156, v[206:209], s[24:25]
	v_mul_f32_e32 v146, v20, v199
	v_mul_f32_e32 v147, v21, v199
	v_mul_f32_e32 v148, v22, v199
	v_mul_f32_e32 v149, v23, v199
	v_mul_f32_e32 v150, v16, v199
	v_mul_f32_e32 v151, v17, v199
	v_mul_f32_e32 v152, v18, v199
	v_mul_f32_e32 v153, v19, v199
	v_add_f32_e32 v146, v146, v138
	v_add_f32_e32 v147, v147, v139
	v_add_f32_e32 v148, v148, v140
	v_add_f32_e32 v149, v149, v141
	v_add_f32_e32 v150, v150, v142
	v_add_f32_e32 v151, v151, v143
	v_add_f32_e32 v152, v152, v144
	v_add_f32_e32 v153, v153, v145
	v_mul_f32_e32 v146, 0xbfb8aa3b, v146
	v_mul_f32_e32 v147, 0xbfb8aa3b, v147
	v_mul_f32_e32 v148, 0xbfb8aa3b, v148
	v_mul_f32_e32 v149, 0xbfb8aa3b, v149
	v_mul_f32_e32 v150, 0xbfb8aa3b, v150
	v_mul_f32_e32 v151, 0xbfb8aa3b, v151
	v_mul_f32_e32 v152, 0xbfb8aa3b, v152
	v_mul_f32_e32 v153, 0xbfb8aa3b, v153
	v_exp_f32_e32 v146, v146
	v_exp_f32_e32 v147, v147
	v_exp_f32_e32 v148, v148
	v_exp_f32_e32 v149, v149
	v_exp_f32_e32 v150, v150
	v_exp_f32_e32 v151, v151
	v_exp_f32_e32 v152, v152
	v_exp_f32_e32 v153, v153
	v_add_f32_e32 v146, 1.0, v146
	v_add_f32_e32 v147, 1.0, v147
	v_add_f32_e32 v148, 1.0, v148
	v_add_f32_e32 v149, 1.0, v149
	v_add_f32_e32 v150, 1.0, v150
	v_add_f32_e32 v151, 1.0, v151
	v_add_f32_e32 v152, 1.0, v152
	v_add_f32_e32 v153, 1.0, v153
	v_rcp_f32_e32 v146, v146
	v_rcp_f32_e32 v147, v147
	v_rcp_f32_e32 v148, v148
	v_rcp_f32_e32 v149, v149
	v_rcp_f32_e32 v150, v150
	v_rcp_f32_e32 v151, v151
	v_rcp_f32_e32 v152, v152
	v_rcp_f32_e32 v153, v153
	v_add_u32_e32 v156, 0x90100, v154
	v_cvt_pk_bf16_f32 v210, v146, v147
	v_cvt_pk_bf16_f32 v211, v148, v149
	v_cvt_pk_bf16_f32 v212, v150, v151
	v_cvt_pk_bf16_f32 v213, v152, v153
	global_store_dwordx4 v156, v[210:213], s[24:25]
	v_mul_f32_e32 v146, v44, v194
	v_mul_f32_e32 v147, v45, v194
	v_mul_f32_e32 v148, v46, v194
	v_mul_f32_e32 v149, v47, v194
	v_mul_f32_e32 v150, v40, v194
	v_mul_f32_e32 v151, v41, v194
	v_mul_f32_e32 v152, v42, v194
	v_mul_f32_e32 v153, v43, v194
	v_add_f32_e32 v146, v146, v130
	v_add_f32_e32 v147, v147, v131
	v_add_f32_e32 v148, v148, v132
	v_add_f32_e32 v149, v149, v133
	v_add_f32_e32 v150, v150, v134
	v_add_f32_e32 v151, v151, v135
	v_add_f32_e32 v152, v152, v136
	v_add_f32_e32 v153, v153, v137
	v_mul_f32_e32 v146, 0xbfb8aa3b, v146
	v_mul_f32_e32 v147, 0xbfb8aa3b, v147
	v_mul_f32_e32 v148, 0xbfb8aa3b, v148
	v_mul_f32_e32 v149, 0xbfb8aa3b, v149
	v_mul_f32_e32 v150, 0xbfb8aa3b, v150
	v_mul_f32_e32 v151, 0xbfb8aa3b, v151
	v_mul_f32_e32 v152, 0xbfb8aa3b, v152
	v_mul_f32_e32 v153, 0xbfb8aa3b, v153
	v_exp_f32_e32 v146, v146
	v_exp_f32_e32 v147, v147
	v_exp_f32_e32 v148, v148
	v_exp_f32_e32 v149, v149
	v_exp_f32_e32 v150, v150
	v_exp_f32_e32 v151, v151
	v_exp_f32_e32 v152, v152
	v_exp_f32_e32 v153, v153
	v_add_f32_e32 v146, 1.0, v146
	v_add_f32_e32 v147, 1.0, v147
	v_add_f32_e32 v148, 1.0, v148
	v_add_f32_e32 v149, 1.0, v149
	v_add_f32_e32 v150, 1.0, v150
	v_add_f32_e32 v151, 1.0, v151
	v_add_f32_e32 v152, 1.0, v152
	v_add_f32_e32 v153, 1.0, v153
	v_rcp_f32_e32 v146, v146
	v_rcp_f32_e32 v147, v147
	v_rcp_f32_e32 v148, v148
	v_rcp_f32_e32 v149, v149
	v_rcp_f32_e32 v150, v150
	v_rcp_f32_e32 v151, v151
	v_rcp_f32_e32 v152, v152
	v_rcp_f32_e32 v153, v153
	v_add_u32_e32 v156, 0xa0000, v154
	v_cvt_pk_bf16_f32 v206, v146, v147
	v_cvt_pk_bf16_f32 v207, v148, v149
	v_cvt_pk_bf16_f32 v208, v150, v151
	v_cvt_pk_bf16_f32 v209, v152, v153
	global_store_dwordx4 v156, v[206:209], s[24:25]
	v_mul_f32_e32 v146, v12, v194
	v_mul_f32_e32 v147, v13, v194
	v_mul_f32_e32 v148, v14, v194
	v_mul_f32_e32 v149, v15, v194
	v_mul_f32_e32 v150, v8, v194
	v_mul_f32_e32 v151, v9, v194
	v_mul_f32_e32 v152, v10, v194
	v_mul_f32_e32 v153, v11, v194
	v_add_f32_e32 v146, v146, v138
	v_add_f32_e32 v147, v147, v139
	v_add_f32_e32 v148, v148, v140
	v_add_f32_e32 v149, v149, v141
	v_add_f32_e32 v150, v150, v142
	v_add_f32_e32 v151, v151, v143
	v_add_f32_e32 v152, v152, v144
; #define LAS __attribute__((address_space(3)))
; DI unsigned pk2(float lo, float hi) { f32x2 v = {lo, hi}; hbf2 r = __builtin_convertvector(v, hbf2); return __builtin_bit_cast(unsigned, r); }
; DI float sigmoidf_(float a) { return fast_rcp(1.0f + fast_exp2(-a * LOG2E)); }
;     DI void operator()(f32x4 (&acc)[2][2][4][2], const Unit& u, int wr, int wc, int fr, int fq, LAS unsigned char* lds) const {
;     ...
;                 int posidx; long offA, offB;
;                 const bool prm = row < TP;
;                 if (prm) { const int b = row >> 13, t = row & 8191; posidx = t;
;                     offA = t >= 8064 ? ((long)(layer * 4 + b) * 128 + (t - 8064)) * 128 : -1;
;                     offB = t >= 7680 ? ((long)(layer * 4 + b) * 512 + (t - 7680)) * 512 : -1;
;                 } else { const int sb = (row - TP) >> 6, t = (row - TP) & 63; posidx = 8192 + t;
;                     offA = ((long)(layer * 32 + sb) * 128 + 64 + t) * 128;
;                     offB = ((long)(layer * 32 + sb) * 512 + 448 + t) * 512; }
;     ...
;                     else { dst = GATES; ld = 2048; c0 = gcol - 2304;
;                         const f32x4 g0 = *(const LAS f32x4*)(lds + BG_OFF + (c0 + cw) * 4), g1 = *(const LAS f32x4*)(lds + BG_OFF + (c0 + cw + 4) * 4);
; #pragma unroll
;                         for (int j = 0; j < 4; ++j) { v0[j] = sigmoidf_(v0[j] + g0[j]); v1[j] = sigmoidf_(v1[j] + g1[j]); } }
;                     u32x4 w; w.x = pk2(v0[0], v0[1]); w.y = pk2(v0[2], v0[3]); w.z = pk2(v1[0], v1[1]); w.w = pk2(v1[2], v1[3]);
;                     *(u32x4*)(dst + (size_t)row * ld + c0 + cw) = w;
	v_add_f32_e32 v153, v153, v145
	v_mul_f32_e32 v146, 0xbfb8aa3b, v146
	v_mul_f32_e32 v147, 0xbfb8aa3b, v147
	v_mul_f32_e32 v148, 0xbfb8aa3b, v148
	v_mul_f32_e32 v149, 0xbfb8aa3b, v149
	v_mul_f32_e32 v150, 0xbfb8aa3b, v150
	v_mul_f32_e32 v151, 0xbfb8aa3b, v151
	v_mul_f32_e32 v152, 0xbfb8aa3b, v152
	v_mul_f32_e32 v153, 0xbfb8aa3b, v153
	v_exp_f32_e32 v146, v146
	v_exp_f32_e32 v147, v147
	v_exp_f32_e32 v148, v148
	v_exp_f32_e32 v149, v149
	v_exp_f32_e32 v150, v150
	v_exp_f32_e32 v151, v151
	v_exp_f32_e32 v152, v152
	v_exp_f32_e32 v153, v153
	v_add_f32_e32 v146, 1.0, v146
	v_add_f32_e32 v147, 1.0, v147
	v_add_f32_e32 v148, 1.0, v148
	v_add_f32_e32 v149, 1.0, v149
	v_add_f32_e32 v150, 1.0, v150
	v_add_f32_e32 v151, 1.0, v151
	v_add_f32_e32 v152, 1.0, v152
	v_add_f32_e32 v153, 1.0, v153
	v_rcp_f32_e32 v146, v146
	v_rcp_f32_e32 v147, v147
	v_rcp_f32_e32 v148, v148
	v_rcp_f32_e32 v149, v149
	v_rcp_f32_e32 v150, v150
	v_rcp_f32_e32 v151, v151
	v_rcp_f32_e32 v152, v152
	v_rcp_f32_e32 v153, v153
	v_add_u32_e32 v156, 0xa0100, v154
	v_cvt_pk_bf16_f32 v210, v146, v147
	v_cvt_pk_bf16_f32 v211, v148, v149
	v_cvt_pk_bf16_f32 v212, v150, v151
	v_cvt_pk_bf16_f32 v213, v152, v153
	global_store_dwordx4 v156, v[210:213], s[24:25]
	v_mul_f32_e32 v146, v36, v195
	v_mul_f32_e32 v147, v37, v195
	v_mul_f32_e32 v148, v38, v195
	v_mul_f32_e32 v149, v39, v195
	v_mul_f32_e32 v150, v32, v195
	v_mul_f32_e32 v151, v33, v195
	v_mul_f32_e32 v152, v34, v195
	v_mul_f32_e32 v153, v35, v195
	v_add_f32_e32 v146, v146, v130
	v_add_f32_e32 v147, v147, v131
	v_add_f32_e32 v148, v148, v132
	v_add_f32_e32 v149, v149, v133
	v_add_f32_e32 v150, v150, v134
	v_add_f32_e32 v151, v151, v135
	v_add_f32_e32 v152, v152, v136
	v_add_f32_e32 v153, v153, v137
	v_mul_f32_e32 v146, 0xbfb8aa3b, v146
	v_mul_f32_e32 v147, 0xbfb8aa3b, v147
	v_mul_f32_e32 v148, 0xbfb8aa3b, v148
	v_mul_f32_e32 v149, 0xbfb8aa3b, v149
	v_mul_f32_e32 v150, 0xbfb8aa3b, v150
	v_mul_f32_e32 v151, 0xbfb8aa3b, v151
	v_mul_f32_e32 v152, 0xbfb8aa3b, v152
	v_mul_f32_e32 v153, 0xbfb8aa3b, v153
	v_exp_f32_e32 v146, v146
	v_exp_f32_e32 v147, v147
	v_exp_f32_e32 v148, v148
	v_exp_f32_e32 v149, v149
	v_exp_f32_e32 v150, v150
	v_exp_f32_e32 v151, v151
	v_exp_f32_e32 v152, v152
	v_exp_f32_e32 v153, v153
	v_add_f32_e32 v146, 1.0, v146
	v_add_f32_e32 v147, 1.0, v147
	v_add_f32_e32 v148, 1.0, v148
	v_add_f32_e32 v149, 1.0, v149
	v_add_f32_e32 v150, 1.0, v150
	v_add_f32_e32 v151, 1.0, v151
	v_add_f32_e32 v152, 1.0, v152
	v_add_f32_e32 v153, 1.0, v153
	v_rcp_f32_e32 v146, v146
	v_rcp_f32_e32 v147, v147
	v_rcp_f32_e32 v148, v148
	v_rcp_f32_e32 v149, v149
	v_rcp_f32_e32 v150, v150
	v_rcp_f32_e32 v151, v151
	v_rcp_f32_e32 v152, v152
	v_rcp_f32_e32 v153, v153
	v_add_u32_e32 v156, 0xb0000, v154
	v_cvt_pk_bf16_f32 v206, v146, v147
	v_cvt_pk_bf16_f32 v207, v148, v149
	v_cvt_pk_bf16_f32 v208, v150, v151
	v_cvt_pk_bf16_f32 v209, v152, v153
	global_store_dwordx4 v156, v[206:209], s[24:25]
	v_mul_f32_e32 v146, v4, v195
	v_mul_f32_e32 v147, v5, v195
	v_mul_f32_e32 v148, v6, v195
	v_mul_f32_e32 v149, v7, v195
	v_mul_f32_e32 v150, v0, v195
	v_mul_f32_e32 v151, v1, v195
	v_mul_f32_e32 v152, v2, v195
	v_mul_f32_e32 v153, v3, v195
	v_add_f32_e32 v146, v146, v138
	v_add_f32_e32 v147, v147, v139
	v_add_f32_e32 v148, v148, v140
	v_add_f32_e32 v149, v149, v141
	v_add_f32_e32 v150, v150, v142
	v_add_f32_e32 v151, v151, v143
	v_add_f32_e32 v152, v152, v144
	v_add_f32_e32 v153, v153, v145
	v_mul_f32_e32 v146, 0xbfb8aa3b, v146
	v_mul_f32_e32 v147, 0xbfb8aa3b, v147
	v_mul_f32_e32 v148, 0xbfb8aa3b, v148
	v_mul_f32_e32 v149, 0xbfb8aa3b, v149
	v_mul_f32_e32 v150, 0xbfb8aa3b, v150
	v_mul_f32_e32 v151, 0xbfb8aa3b, v151
	v_mul_f32_e32 v152, 0xbfb8aa3b, v152
	v_mul_f32_e32 v153, 0xbfb8aa3b, v153
	v_exp_f32_e32 v146, v146
	v_exp_f32_e32 v147, v147
	v_exp_f32_e32 v148, v148
	v_exp_f32_e32 v149, v149
	v_exp_f32_e32 v150, v150
	v_exp_f32_e32 v151, v151
	v_exp_f32_e32 v152, v152
	v_exp_f32_e32 v153, v153
	v_add_f32_e32 v146, 1.0, v146
	v_add_f32_e32 v147, 1.0, v147
	v_add_f32_e32 v148, 1.0, v148
	v_add_f32_e32 v149, 1.0, v149
	v_add_f32_e32 v150, 1.0, v150
	v_add_f32_e32 v151, 1.0, v151
	v_add_f32_e32 v152, 1.0, v152
	v_add_f32_e32 v153, 1.0, v153
	v_rcp_f32_e32 v146, v146
	v_rcp_f32_e32 v147, v147
	v_rcp_f32_e32 v148, v148
	v_rcp_f32_e32 v149, v149
	v_rcp_f32_e32 v150, v150
	v_rcp_f32_e32 v151, v151
	v_rcp_f32_e32 v152, v152
	v_rcp_f32_e32 v153, v153
	v_add_u32_e32 v156, 0xb0100, v154
	v_cvt_pk_bf16_f32 v210, v146, v147
	v_cvt_pk_bf16_f32 v211, v148, v149
	v_cvt_pk_bf16_f32 v212, v150, v151
	v_cvt_pk_bf16_f32 v213, v152, v153
	global_store_dwordx4 v156, v[210:213], s[24:25]
	s_mov_b64 s[22:23], exec
	s_branch .LBB0_639
.Lepf_none:
	v_add_u32_e32 v96, 0xffff8000, v192
	s_movk_i32 s0, 0x7fff
	v_lshrrev_b32_e32 v96, 6, v96
	v_cmp_lt_i32_e32 vcc, s0, v192
	v_readlane_b32 s0, v246, 32
	s_waitcnt lgkmcnt(0)
	v_mov_b32_e32 v206, v221
	v_mov_b32_e32 v200, v205
	v_mov_b32_e32 v196, v199
	v_mov_b32_e32 v188, v195
	v_add_u32_e32 v202, s0, v96
	s_and_saveexec_b64 s[0:1], vcc
	s_xor_b64 s[22:23], exec, s[0:1]
	v_mov_b32_e32 v203, v97
	v_lshlrev_b64 v[208:209], 14, v[202:203]
	v_lshlrev_b64 v[214:215], 18, v[202:203]
	v_or_b32_e32 v208, v208, v168
	v_or_b32_e32 v214, v214, v170
	s_or_saveexec_b64 s[22:23], s[22:23]
	v_ashrrev_i32_e32 v189, 13, v192
	v_mov_b64_e32 v[210:211], 0x2640000
	v_mov_b64_e32 v[212:213], 0x2740000
	v_mov_b64_e32 v[216:217], 0x2840000
	v_mov_b64_e32 v[218:219], 0x3840000
	v_mov_b32_e32 v130, v177
	s_xor_b64 exec, exec, s[22:23]
	s_cbranch_execz .LBB0_205
	v_and_b32_e32 v130, 0x1fcf, v192
	s_movk_i32 s0, 0x1f7f
	v_cmp_lt_u32_e32 vcc, s0, v130
	v_mov_b64_e32 v[214:215], -1
	v_mov_b64_e32 v[208:209], -1
	s_and_saveexec_b64 s[24:25], vcc
	v_add_u32_e32 v132, s92, v189
	v_ashrrev_i32_e32 v133, 31, v132
	v_add_u32_e32 v96, 0xffffe080, v130
	v_lshlrev_b64 v[132:133], 14, v[132:133]
	v_lshlrev_b64 v[134:135], 7, v[96:97]
	v_lshl_add_u64 v[208:209], v[132:133], 0, v[134:135]
	s_or_b64 exec, exec, s[24:25]
	s_movk_i32 s0, 0x1dff
	v_cmp_lt_u32_e32 vcc, s0, v130
	s_and_saveexec_b64 s[24:25], vcc
	v_add_u32_e32 v132, s92, v189
	v_ashrrev_i32_e32 v133, 31, v132
	v_add_u32_e32 v96, 0xffffe200, v130
	v_lshlrev_b64 v[132:133], 18, v[132:133]
	v_lshlrev_b64 v[134:135], 9, v[96:97]
	v_lshl_add_u64 v[214:215], v[132:133], 0, v[134:135]
	s_or_b64 exec, exec, s[24:25]
	v_mov_b64_e32 v[210:211], 0x2200000
	v_mov_b64_e32 v[212:213], 0x2220000
	v_mov_b64_e32 v[216:217], 0x2240000
	v_mov_b64_e32 v[218:219], 0x2440000
